# RWKV: waves 4-7 (idle in phase A) L2-prefetch the current group's 128 rows and the next group's first rows (on v52)
# baseline (speedup 1.0000x reference)
; __device__ __forceinline__ float bf2f(bf16_t v) { return __uint_as_float(((unsigned)v) << 16); }
; __device__ __forceinline__ void rwkv_phaseA(const Ctx& F, LAS unsigned char* W, unsigned char* X, int b, int h, int c) {
;     ...
;         const size_t row0 = (size_t)b * S + c * 32;
;         const bf16_t* pb = proj + row0 * IN_EVEN_P + RW_OFF + h * 64; const bf16_t* lb = LO + row0 * 1536 + h * 64;
;         float pr_ = 0.f, pk_ = 0.f, pv_ = 0.f;
;         if (c > 0) { const bf16_t* pp = pb - IN_EVEN_P; pr_ = bf2f(pp[ul0]); pk_ = bf2f(pp[512 + ul0]); pv_ = bf2f(pp[1024 + ul0]); }
;         bf16_t cur[8][5], nxt[8][5];
; __device__ __forceinline__ void rwkv_chunked_bh(const Ctx& F, int b, int h) {
;     ...
;     for (int grp = 0; grp < S / 32 / RG; ++grp) {
;         __syncthreads();
;         if (w < RG) rwkv_phaseA(F, L + w * RA_BYTES, XS + w * RX_BYTES, b, h, grp * RG + w);
.Lrw_pf:
	s_sub_i32 s32, s50, 4
	s_lshl_b32 s32, s32, 6
	v_add_u32_e32 v150, s32, v71
	v_and_b32_e32 v152, 7, v150
	v_lshrrev_b32_e32 v151, 3, v150
	s_lshl_b32 s32, s22, 7
	s_add_u32 s32, s38, s32
	s_movk_i32 s100, 0x1400
	s_movk_i32 s101, 0xc00
	v_add_u32_e32 v153, s32, v151
	v_cmp_lt_u32_e32 vcc, 5, v152
	v_lshrrev_b32_e32 v156, 1, v152
	v_and_b32_e32 v158, 1, v152
	v_lshlrev_b32_e32 v156, 10, v156
	v_lshl_add_u32 v154, v158, 6, v156
	v_lshlrev_b32_e32 v156, 10, v158
	v_mul_lo_u32 v159, v153, s100
	v_mul_lo_u32 v153, v153, s101
	s_lshl_b32 s32, s14, 1
	s_add_u32 s32, s32, 0xc200540
	v_add3_u32 v154, v159, v154, s32
	v_add_u32_e32 v156, v153, v156
	v_mov_b32_e32 v155, 0
	v_mov_b32_e32 v157, 0
	s_mov_b32 s98, s15
	s_mov_b32 s99, s70
	v_lshl_add_u64 v[160:161], s[46:47], 0, v[154:155]
	v_lshl_add_u64 v[162:163], s[98:99], 0, v[156:157]
	v_mov_b32_e32 v166, 0x28000
	v_mov_b32_e32 v167, 0x18000
	v_cndmask_b32_e32 v160, v160, v162, vcc
	v_cndmask_b32_e32 v161, v161, v163, vcc
	v_cndmask_b32_e32 v164, v166, v167, vcc
	v_mov_b32_e32 v165, 0
	v_mov_b32_e32 v166, 0x1400
	v_mov_b32_e32 v167, 0xc00
	v_cndmask_b32_e32 v166, v166, v167, vcc
	v_mov_b64_e32 v[168:169], v[160:161]
	global_load_dword v170, v[160:161], off
	v_lshl_add_u64 v[160:161], v[160:161], 0, v[164:165]
	global_load_dword v171, v[160:161], off
	v_lshl_add_u64 v[160:161], v[160:161], 0, v[164:165]
	global_load_dword v172, v[160:161], off
	v_lshl_add_u64 v[160:161], v[160:161], 0, v[164:165]
	global_load_dword v173, v[160:161], off
	s_cmp_eq_u32 s22, 15
	s_cbranch_scc1 .LBB0_833
	v_lshrrev_b32_e32 v162, 6, v150
	v_mul_u32_u24_e32 v162, 24, v162
	v_add_u32_e32 v162, 0x80, v162
	v_mul_u32_u24_e32 v162, v162, v166
	v_mov_b32_e32 v163, 0
	v_lshl_add_u64 v[168:169], v[168:169], 0, v[162:163]
	global_load_dword v174, v[168:169], off
